# NSA selected branch constant-bias tiles: max on raw scores, scale+bias folded into the exp argument (one fma), packed row sums, fewer max ops; all math still f32
# baseline (speedup 1.0000x reference)
.LBB0_439:
	s_andn2_b64 vcc, exec, s[6:7]
	s_cbranch_vccnz .LBB0_448
	v_and_b32_e32 v0, 1, v164
	v_cmp_eq_u32_e64 s[42:43], 1, v0
	v_and_b32_e32 v0, 1, v162
	v_cmp_eq_u32_e64 s[44:45], 1, v0
	s_or_b64 s[6:7], s[44:45], s[42:43]
	v_cndmask_b32_e64 v54, 0, 1, s[6:7]
	v_cmp_ne_u32_e32 vcc, 0, v54
	s_cbranch_vccz .Lsel_fast
	v_add_u32_e32 v54, s13, v196
	v_cmp_ne_u32_e32 vcc, 0, v0
	v_add_u32_e32 v62, v54, v194
	v_add_u32_e32 v0, v54, v195
	s_cbranch_vccz .LBB0_444
	ds_read_b128 v[54:57], v62 offset:16384
	ds_read_b32 v80, v193
	ds_read_b128 v[58:61], v62 offset:18432
	ds_read_b128 v[64:67], v62 offset:20480
	ds_read_b128 v[68:71], v0 offset:16384
	ds_read_b128 v[72:75], v62 offset:22528
	s_waitcnt lgkmcnt(0)
	v_mfma_f32_16x16x32_bf16 v[54:57], v[54:57], v[2:5], 0
	v_mfma_f32_16x16x32_bf16 v[58:61], v[58:61], v[2:5], 0
	v_mfma_f32_16x16x32_bf16 v[54:57], v[68:71], v[6:9], v[54:57]
	ds_read_b128 v[68:71], v0 offset:18432
	ds_read_b128 v[76:79], v0 offset:20480
	v_mfma_f32_16x16x32_bf16 v[64:67], v[64:67], v[2:5], 0
	v_mfma_f32_16x16x32_bf16 v[84:87], v[72:75], v[2:5], 0
	s_waitcnt lgkmcnt(0)
	v_mfma_f32_16x16x32_bf16 v[58:61], v[68:71], v[6:9], v[58:61]
	ds_read_b128 v[68:71], v0 offset:22528
	v_mfma_f32_16x16x32_bf16 v[64:67], v[76:79], v[6:9], v[64:67]
	s_waitcnt lgkmcnt(0)
	v_mfma_f32_16x16x32_bf16 v[84:87], v[68:71], v[6:9], v[84:87]
	v_max3_f32 v63, v54, v55, v56
	s_nop 2
	v_max3_f32 v63, v63, v57, v58
	v_max3_f32 v63, v63, v59, v60
	v_max3_f32 v63, v63, v61, v64
	v_max3_f32 v63, v63, v65, v66
	v_max3_f32 v63, v63, v67, v84
	v_max3_f32 v63, v63, v85, v86
	v_max_f32_e32 v63, v63, v87
	ds_bpermute_b32 v68, v119, v63
	s_waitcnt lgkmcnt(0)
	v_max_f32_e32 v63, v63, v68
	ds_bpermute_b32 v68, v137, v63
	s_waitcnt lgkmcnt(0)
	v_max_f32_e32 v63, v63, v68
	v_fma_f32 v63, v63, s36, v80
	v_max_f32_e32 v63, s29, v63
	v_cndmask_b32_e64 v63, v148, v63, s[44:45]
	v_max_f32_e32 v68, v160, v63
	v_sub_f32_e32 v69, v160, v68
	v_exp_f32_e32 v70, v69
	v_cndmask_b32_e64 v63, v209, v68, s[44:45]
	v_mov_b32_e32 v160, v68
	v_sub_f32_e32 v82, v80, v63
	v_pk_mul_f32 v[36:37], v[36:37], v[70:71] op_sel_hi:[1,0]
	v_pk_mul_f32 v[34:35], v[34:35], v[70:71] op_sel_hi:[1,0]
	v_pk_mul_f32 v[48:49], v[48:49], v[70:71] op_sel_hi:[1,0]
	v_pk_mul_f32 v[46:47], v[46:47], v[70:71] op_sel_hi:[1,0]
	v_pk_mul_f32 v[44:45], v[44:45], v[70:71] op_sel_hi:[1,0]
	v_pk_mul_f32 v[42:43], v[42:43], v[70:71] op_sel_hi:[1,0]
	v_pk_mul_f32 v[52:53], v[52:53], v[70:71] op_sel_hi:[1,0]
	v_pk_mul_f32 v[50:51], v[50:51], v[70:71] op_sel_hi:[1,0]
	v_pk_fma_f32 v[54:55], v[54:55], s[36:37], v[82:83] op_sel_hi:[1,0,0]
	v_pk_fma_f32 v[56:57], v[56:57], s[36:37], v[82:83] op_sel_hi:[1,0,0]
	v_pk_fma_f32 v[58:59], v[58:59], s[36:37], v[82:83] op_sel_hi:[1,0,0]
	v_pk_fma_f32 v[60:61], v[60:61], s[36:37], v[82:83] op_sel_hi:[1,0,0]
	v_pk_fma_f32 v[64:65], v[64:65], s[36:37], v[82:83] op_sel_hi:[1,0,0]
	v_pk_fma_f32 v[66:67], v[66:67], s[36:37], v[82:83] op_sel_hi:[1,0,0]
	v_pk_fma_f32 v[84:85], v[84:85], s[36:37], v[82:83] op_sel_hi:[1,0,0]
	v_pk_fma_f32 v[86:87], v[86:87], s[36:37], v[82:83] op_sel_hi:[1,0,0]
	v_exp_f32_e32 v54, v54
	v_exp_f32_e32 v55, v55
	v_exp_f32_e32 v56, v56
	v_exp_f32_e32 v57, v57
	v_exp_f32_e32 v58, v58
	v_exp_f32_e32 v59, v59
	v_exp_f32_e32 v60, v60
	v_exp_f32_e32 v61, v61
	v_exp_f32_e32 v64, v64
	v_exp_f32_e32 v65, v65
	v_exp_f32_e32 v66, v66
	v_exp_f32_e32 v67, v67
	v_exp_f32_e32 v84, v84
	v_exp_f32_e32 v85, v85
	v_exp_f32_e32 v86, v86
	v_exp_f32_e32 v87, v87
	s_nop 0
	v_pk_add_f32 v[72:73], v[54:55], v[56:57]
	v_pk_add_f32 v[74:75], v[58:59], v[60:61]
	v_pk_add_f32 v[76:77], v[64:65], v[66:67]
	v_pk_add_f32 v[78:79], v[84:85], v[86:87]
	v_pk_add_f32 v[72:73], v[72:73], v[74:75]
	v_pk_add_f32 v[76:77], v[76:77], v[78:79]
	s_nop 0
	v_pk_add_f32 v[72:73], v[72:73], v[76:77]
	s_nop 0
	v_add_f32_e32 v72, v72, v73
	v_fma_f32 v144, v144, v70, v72
	v_cvt_pk_bf16_f32 v61, v60, v61
	v_cvt_pk_bf16_f32 v60, v58, v59
	v_cvt_pk_bf16_f32 v59, v56, v57
	v_cvt_pk_bf16_f32 v58, v54, v55
	v_cvt_pk_bf16_f32 v54, v64, v65
	v_cvt_pk_bf16_f32 v55, v66, v67
	v_cvt_pk_bf16_f32 v56, v84, v85
	v_cvt_pk_bf16_f32 v57, v86, v87
	v_cndmask_b32_e64 v63, 0, 1, s[42:43]
	v_cmp_ne_u32_e32 vcc, 0, v63
	s_cbranch_vccz .LBB0_445
.LBB0_443:
	ds_read_b128 v[64:67], v62 offset:16384
	ds_read_b128 v[68:71], v62 offset:18432
	ds_read_b128 v[72:75], v0 offset:16384
	ds_read_b128 v[76:79], v0 offset:18432
	s_waitcnt lgkmcnt(0)
	v_mfma_f32_16x16x32_bf16 v[64:67], v[64:67], v[10:13], 0
	v_mfma_f32_16x16x32_bf16 v[68:71], v[68:71], v[10:13], 0
	v_mfma_f32_16x16x32_bf16 v[64:67], v[72:75], v[14:17], v[64:67]
	ds_read_b128 v[72:75], v62 offset:20480
	v_mfma_f32_16x16x32_bf16 v[68:71], v[76:79], v[14:17], v[68:71]
	ds_read_b128 v[76:79], v0 offset:20480
	ds_read_b128 v[80:83], v62 offset:22528
	ds_read_b32 v88, v193
	ds_read_b128 v[84:87], v0 offset:22528
	s_waitcnt lgkmcnt(0)
	v_mfma_f32_16x16x32_bf16 v[72:75], v[72:75], v[10:13], 0
	v_mfma_f32_16x16x32_bf16 v[80:83], v[80:83], v[10:13], 0
	v_mfma_f32_16x16x32_bf16 v[72:75], v[76:79], v[14:17], v[72:75]
	v_mfma_f32_16x16x32_bf16 v[80:83], v[84:87], v[14:17], v[80:83]
	v_max3_f32 v76, v64, v65, v66
	v_max3_f32 v76, v76, v67, v68
	v_max3_f32 v76, v76, v69, v70
	v_max_f32_e32 v76, v76, v71
	s_nop 3
	v_max3_f32 v76, v76, v72, v73
	v_max3_f32 v76, v76, v74, v75
	v_max3_f32 v76, v76, v80, v81
	v_max3_f32 v76, v76, v82, v83
	ds_bpermute_b32 v77, v119, v76
	s_waitcnt lgkmcnt(0)
	v_max_f32_e32 v76, v76, v77
	ds_bpermute_b32 v77, v137, v76
	s_waitcnt lgkmcnt(0)
	v_max_f32_e32 v76, v76, v77
	v_fma_f32 v76, v76, s36, v88
	v_max_f32_e32 v76, s29, v76
	v_cndmask_b32_e64 v76, v148, v76, s[42:43]
	v_max_f32_e32 v77, v161, v76
	v_sub_f32_e32 v0, v161, v77
	v_exp_f32_e32 v0, v0
	v_cndmask_b32_e64 v78, v209, v77, s[42:43]
	v_mov_b32_e32 v161, v77
	v_sub_f32_e32 v78, v88, v78
	v_pk_mul_f32 v[32:33], v[32:33], v[0:1] op_sel_hi:[1,0]
	v_pk_mul_f32 v[30:31], v[30:31], v[0:1] op_sel_hi:[1,0]
	v_pk_mul_f32 v[28:29], v[28:29], v[0:1] op_sel_hi:[1,0]
	v_pk_mul_f32 v[26:27], v[26:27], v[0:1] op_sel_hi:[1,0]
	v_pk_mul_f32 v[24:25], v[24:25], v[0:1] op_sel_hi:[1,0]
	v_pk_mul_f32 v[22:23], v[22:23], v[0:1] op_sel_hi:[1,0]
	v_pk_mul_f32 v[20:21], v[20:21], v[0:1] op_sel_hi:[1,0]
	v_pk_mul_f32 v[18:19], v[18:19], v[0:1] op_sel_hi:[1,0]
	v_pk_fma_f32 v[64:65], v[64:65], s[36:37], v[78:79] op_sel_hi:[1,0,0]
	v_pk_fma_f32 v[66:67], v[66:67], s[36:37], v[78:79] op_sel_hi:[1,0,0]
	v_pk_fma_f32 v[68:69], v[68:69], s[36:37], v[78:79] op_sel_hi:[1,0,0]
	v_pk_fma_f32 v[70:71], v[70:71], s[36:37], v[78:79] op_sel_hi:[1,0,0]
	v_pk_fma_f32 v[72:73], v[72:73], s[36:37], v[78:79] op_sel_hi:[1,0,0]
	v_pk_fma_f32 v[74:75], v[74:75], s[36:37], v[78:79] op_sel_hi:[1,0,0]
	v_pk_fma_f32 v[80:81], v[80:81], s[36:37], v[78:79] op_sel_hi:[1,0,0]
	v_pk_fma_f32 v[82:83], v[82:83], s[36:37], v[78:79] op_sel_hi:[1,0,0]
	v_exp_f32_e32 v64, v64
	v_exp_f32_e32 v65, v65
	v_exp_f32_e32 v66, v66
	v_exp_f32_e32 v67, v67
	v_exp_f32_e32 v68, v68
	v_exp_f32_e32 v69, v69
	v_exp_f32_e32 v70, v70
	v_exp_f32_e32 v71, v71
	v_exp_f32_e32 v72, v72
	v_exp_f32_e32 v73, v73
	v_exp_f32_e32 v74, v74
	v_exp_f32_e32 v75, v75
	v_exp_f32_e32 v80, v80
	v_exp_f32_e32 v81, v81
	v_exp_f32_e32 v82, v82
	v_exp_f32_e32 v83, v83
	s_nop 0
	v_pk_add_f32 v[84:85], v[64:65], v[66:67]
	v_pk_add_f32 v[86:87], v[68:69], v[70:71]
	v_pk_add_f32 v[76:77], v[72:73], v[74:75]
	v_pk_add_f32 v[78:79], v[80:81], v[82:83]
	v_pk_add_f32 v[84:85], v[84:85], v[86:87]
	v_pk_add_f32 v[76:77], v[76:77], v[78:79]
	s_nop 0
	v_pk_add_f32 v[84:85], v[84:85], v[76:77]
	s_nop 0
	v_add_f32_e32 v84, v84, v85
	v_fma_f32 v145, v145, v0, v84
	v_cvt_pk_bf16_f32 v67, v66, v67
	v_cvt_pk_bf16_f32 v66, v64, v65
	v_cvt_pk_bf16_f32 v68, v68, v69
	v_cvt_pk_bf16_f32 v69, v70, v71
	v_cvt_pk_bf16_f32 v62, v72, v73
	v_cvt_pk_bf16_f32 v63, v74, v75
	v_cvt_pk_bf16_f32 v64, v80, v81
	v_cvt_pk_bf16_f32 v65, v82, v83
	s_branch .LBB0_446
